# first grid barrier reads its 16 arrival counters with all loads in flight; mlstm_out Q/K/V staging loads issued up front; smp_ssd dt-row prefetch
# speedup vs baseline: 1.0987x; 1.0021x over previous
.LBB0_69:
	v_readlane_b32 s4, v241, 52
	v_readlane_b32 s5, v241, 53
	v_readlane_b32 s6, v241, 49
	s_waitcnt lgkmcnt(0)
	s_nop 2
	global_load_dword v0, v169, s[4:5] sc1
	v_readlane_b32 s4, v241, 54
	v_readlane_b32 s5, v241, 55
	s_nop 4
	global_load_dword v1, v169, s[4:5] sc1
	v_readlane_b32 s4, v241, 56
	v_readlane_b32 s5, v241, 57
	s_nop 1
	s_nop 2
	global_load_dword v2, v169, s[4:5] sc1
	v_readlane_b32 s4, v241, 58
	v_readlane_b32 s5, v241, 59
	s_nop 1
	s_nop 2
	global_load_dword v3, v169, s[4:5] sc1
	v_readlane_b32 s4, v241, 60
	v_readlane_b32 s5, v241, 61
	s_nop 1
	s_nop 2
	global_load_dword v4, v169, s[4:5] sc1
	v_readlane_b32 s4, v241, 62
	v_readlane_b32 s5, v241, 63
	s_nop 1
	s_nop 2
	global_load_dword v5, v169, s[4:5] sc1
	v_readlane_b32 s4, v240, 0
	v_readlane_b32 s5, v240, 1
	s_nop 1
	s_nop 2
	global_load_dword v6, v169, s[4:5] sc1
	v_readlane_b32 s4, v240, 2
	v_readlane_b32 s5, v240, 3
	s_nop 1
	s_nop 2
	global_load_dword v7, v169, s[4:5] sc1
	v_readlane_b32 s4, v240, 4
	v_readlane_b32 s5, v240, 5
	s_nop 1
	s_nop 2
	global_load_dword v8, v169, s[4:5] sc1
	v_readlane_b32 s4, v240, 6
	v_readlane_b32 s5, v240, 7
	s_nop 1
	s_nop 2
	global_load_dword v9, v169, s[4:5] sc1
	v_readlane_b32 s4, v240, 8
	v_readlane_b32 s5, v240, 9
	s_nop 1
	s_nop 2
	global_load_dword v10, v169, s[4:5] sc1
	v_readlane_b32 s4, v240, 10
	v_readlane_b32 s5, v240, 11
	s_nop 1
	s_nop 2
	global_load_dword v11, v169, s[4:5] sc1
	v_readlane_b32 s4, v240, 12
	v_readlane_b32 s5, v240, 13
	s_nop 1
	s_nop 2
	global_load_dword v12, v169, s[4:5] sc1
	v_readlane_b32 s4, v240, 14
	v_readlane_b32 s5, v240, 15
	s_nop 1
	s_nop 2
	global_load_dword v13, v169, s[4:5] sc1
	v_readlane_b32 s4, v240, 16
	v_readlane_b32 s5, v240, 17
	s_nop 1
	s_nop 2
	global_load_dword v14, v169, s[4:5] sc1
	v_readlane_b32 s4, v240, 18
	v_readlane_b32 s5, v240, 19
	s_nop 1
	s_nop 2
	global_load_dword v15, v169, s[4:5] sc1
	s_mov_b64 s[4:5], -1
	s_nop 1
	s_waitcnt vmcnt(0)
	v_add_u32_e32 v16, v1, v0
	v_add_u32_e32 v16, v16, v2
	v_add_u32_e32 v16, v16, v3
	v_add_u32_e32 v16, v16, v4
	v_add_u32_e32 v16, v16, v5
	v_add_u32_e32 v16, v16, v6
	v_add_u32_e32 v16, v16, v7
	v_add_u32_e32 v16, v16, v8
	v_add_u32_e32 v16, v16, v9
	v_add_u32_e32 v16, v16, v10
	v_add_u32_e32 v16, v16, v11
	v_add_u32_e32 v16, v16, v12
	v_add_u32_e32 v16, v16, v13
	v_add_u32_e32 v16, v16, v14
	v_add_u32_e32 v16, v16, v15
	v_cmp_eq_u32_e32 vcc, s6, v16
	s_mov_b64 s[6:7], -1
	s_cbranch_vccnz .LBB0_68
	s_and_b32 s4, s13, 0xff
	s_cmp_eq_u32 s4, 0
	s_mov_b64 s[4:5], -1
	s_mov_b64 s[8:9], -1
	s_sleep 1
	s_cbranch_scc0 .LBB0_73
	v_readlane_b32 s4, v241, 50
	v_readlane_b32 s5, v241, 51
	s_nop 4
	global_load_dword v16, v169, s[4:5] sc1
	s_waitcnt vmcnt(0)
	v_cmp_eq_u32_e32 vcc, 0, v16
	s_cbranch_vccnz .LBB0_75
	s_mov_b64 s[8:9], 0
	s_mov_b64 s[4:5], -1

.LBB0_283:
	s_ashr_i32 s12, s30, 1
	s_lshl_b32 s68, s12, 3
	s_addk_i32 s68, 0x2000
	s_and_b32 s70, s30, 1
	s_mul_i32 s3, s68, 0x3600
	v_mov_b32_e32 v97, v178
	s_mul_hi_i32 s2, s68, 0x3600
	s_add_u32 s6, s80, s3
	s_addc_u32 s7, s81, s2
	v_cmp_gt_i32_e32 vcc, 64, v97
	v_ashrrev_i32_e32 v71, 3, v97
	v_and_b32_e32 v70, 7, v97
	v_lshl_add_u32 v91, v97, 2, 0
	s_and_saveexec_b64 s[8:9], vcc
	s_cbranch_execz .LBB0_286
	v_lshl_add_u32 v0, s70, 3, v71
	v_add_u32_e32 v2, s96, v0
	v_ashrrev_i32_e32 v3, 31, v2
	v_readlane_b32 s36, v241, 11
	v_lshlrev_b64 v[4:5], 2, v[2:3]
	v_readlane_b32 s50, v241, 25
	v_readlane_b32 s51, v241, 26
	v_readlane_b32 s48, v241, 23
	v_readlane_b32 s49, v241, 24
	v_lshl_add_u64 v[2:3], s[50:51], 0, v[4:5]
	global_load_dword v1, v[2:3], off
	v_lshl_add_u64 v[4:5], s[48:49], 0, v[4:5]
	s_movk_i32 s2, 0x3000
	global_load_dword v3, v[4:5], off
	v_readlane_b32 s37, v241, 12
	v_readlane_b32 s38, v241, 13
	v_readlane_b32 s39, v241, 14
	v_readlane_b32 s40, v241, 15
	v_readlane_b32 s41, v241, 16
	v_readlane_b32 s42, v241, 17
	v_readlane_b32 s43, v241, 18
	v_readlane_b32 s44, v241, 19
	v_readlane_b32 s45, v241, 20
	v_readlane_b32 s46, v241, 21
	v_readlane_b32 s47, v241, 22
	s_waitcnt vmcnt(1)
	v_mul_f32_e32 v1, 0x3fb8aa3b, v1
	v_exp_f32_e32 v2, v1
	v_ashrrev_i32_e32 v1, 31, v0
	v_lshl_add_u64 v[0:1], v[0:1], 1, s[6:7]
	v_add_co_u32_e32 v248, vcc, 0x6600, v0
	s_nop 1
	v_addc_co_u32_e32 v249, vcc, 0, v1, vcc
	global_load_ushort v244, v[248:249], off offset:1040
	v_add_co_u32_e32 v248, vcc, 0x3600, v248
	s_nop 1
	v_addc_co_u32_e32 v249, vcc, 0, v249, vcc
	global_load_ushort v244, v[248:249], off offset:1040
	v_add_co_u32_e32 v248, vcc, 0x3600, v248
	s_nop 1
	v_addc_co_u32_e32 v249, vcc, 0, v249, vcc
	global_load_ushort v244, v[248:249], off offset:1040
	v_add_co_u32_e32 v248, vcc, 0x3600, v248
	s_nop 1
	v_addc_co_u32_e32 v249, vcc, 0, v249, vcc
	global_load_ushort v244, v[248:249], off offset:1040
	v_add_co_u32_e32 v248, vcc, 0x3600, v248
	s_nop 1
	v_addc_co_u32_e32 v249, vcc, 0, v249, vcc
	global_load_ushort v244, v[248:249], off offset:1040
	v_add_co_u32_e32 v248, vcc, 0x3600, v248
	s_nop 1
	v_addc_co_u32_e32 v249, vcc, 0, v249, vcc
	global_load_ushort v244, v[248:249], off offset:1040
	v_add_co_u32_e32 v248, vcc, 0x3600, v248
	s_nop 1
	v_addc_co_u32_e32 v249, vcc, 0, v249, vcc
	global_load_ushort v244, v[248:249], off offset:1040
	v_add_co_u32_e32 v4, vcc, s2, v0
	s_nop 1
	v_addc_co_u32_e32 v5, vcc, 0, v1, vcc
	global_load_ushort v4, v[4:5], off offset:1040
	s_waitcnt vmcnt(0)
	v_lshlrev_b32_e32 v4, 16, v4
	v_add_f32_e32 v4, v3, v4
	v_max_f32_e32 v5, 0, v4
	v_mul_f32_e64 v4, |v4|, s59
	v_exp_f32_e32 v4, v4
	s_nop 0
	v_add_f32_e32 v4, 1.0, v4
	v_cmp_gt_f32_e32 vcc, s60, v4
	s_nop 1
	v_cndmask_b32_e64 v6, 0, 32, vcc
	v_ldexp_f32 v4, v4, v6
	v_log_f32_e32 v4, v4
	s_nop 0
	v_mul_f32_e32 v6, 0x3f317217, v4
	v_fma_f32 v6, v4, s61, -v6
	v_fmac_f32_e32 v6, 0x3377d1cf, v4
	v_fmac_f32_e32 v6, 0x3f317217, v4
	v_cmp_lt_f32_e64 s[2:3], |v4|, s62
	s_nop 1
	v_cndmask_b32_e64 v4, v4, v6, s[2:3]
	v_cndmask_b32_e32 v6, 0, v186, vcc
	v_sub_f32_e32 v4, v4, v6
	v_add_f32_e32 v4, v5, v4
	v_cmp_eq_u32_e32 vcc, 0, v70
	s_movk_i32 s2, 0x6000
	v_fma_f32 v6, -v2, v4, 0
	v_cndmask_b32_e32 v7, 0, v4, vcc
	v_add_co_u32_e64 v4, s[2:3], s2, v0
	s_nop 1
	v_addc_co_u32_e64 v5, s[2:3], 0, v1, s[2:3]
	global_load_ushort v4, v[4:5], off offset:2576
	s_waitcnt vmcnt(0)
	v_lshlrev_b32_e32 v4, 16, v4
	v_add_f32_e32 v4, v3, v4
	v_max_f32_e32 v5, 0, v4
	v_mul_f32_e64 v4, |v4|, s59
	v_exp_f32_e32 v4, v4
	s_nop 0
	v_add_f32_e32 v4, 1.0, v4
	v_cmp_gt_f32_e64 s[2:3], s60, v4
	s_nop 1
	v_cndmask_b32_e64 v8, 0, 32, s[2:3]
	v_ldexp_f32 v4, v4, v8
	v_log_f32_e32 v4, v4
	s_nop 0
	v_mul_f32_e32 v8, 0x3f317217, v4
	v_fma_f32 v8, v4, s61, -v8
	v_fmac_f32_e32 v8, 0x3377d1cf, v4
	v_fmac_f32_e32 v8, 0x3f317217, v4
	v_cmp_lt_f32_e64 s[4:5], |v4|, s62
	s_nop 1
	v_cndmask_b32_e64 v4, v4, v8, s[4:5]
	v_cndmask_b32_e64 v8, 0, v186, s[2:3]
	v_sub_f32_e32 v4, v4, v8
	v_add_f32_e32 v5, v5, v4
	v_cmp_eq_u32_e64 s[2:3], 1, v70
	v_fma_f32 v4, -v2, v5, v6
	v_cndmask_b32_e32 v8, v4, v6, vcc
	v_cndmask_b32_e64 v9, v7, v5, s[2:3]
	s_mov_b32 s2, 0xa000
	v_add_co_u32_e64 v6, s[2:3], s2, v0
	s_nop 1
	v_addc_co_u32_e64 v7, s[2:3], 0, v1, s[2:3]
	global_load_ushort v5, v[6:7], off offset:16
	s_waitcnt vmcnt(0)
	v_lshlrev_b32_e32 v5, 16, v5
	v_add_f32_e32 v5, v3, v5
	v_max_f32_e32 v6, 0, v5
	v_mul_f32_e64 v5, |v5|, s59
	v_exp_f32_e32 v5, v5
	s_nop 0
	v_add_f32_e32 v5, 1.0, v5
	v_cmp_gt_f32_e64 s[2:3], s60, v5
	s_nop 1
	v_cndmask_b32_e64 v7, 0, 32, s[2:3]
	v_ldexp_f32 v5, v5, v7
	v_log_f32_e32 v5, v5
	s_nop 0
	v_mul_f32_e32 v7, 0x3f317217, v5
	v_fma_f32 v7, v5, s61, -v7
	v_fmac_f32_e32 v7, 0x3377d1cf, v5
	v_fmac_f32_e32 v7, 0x3f317217, v5
	v_cmp_lt_f32_e64 s[4:5], |v5|, s62
	s_nop 1
	v_cndmask_b32_e64 v5, v5, v7, s[4:5]
	v_cndmask_b32_e64 v7, 0, v186, s[2:3]
	v_sub_f32_e32 v5, v5, v7
	v_add_f32_e32 v5, v6, v5
	v_cmp_gt_u32_e64 s[2:3], 2, v70
	v_fma_f32 v6, v5, -v2, v8
	s_nop 0
	v_cndmask_b32_e64 v8, v6, v8, s[2:3]
	v_cmp_eq_u32_e64 s[2:3], 2, v70
	s_nop 1
	v_cndmask_b32_e64 v9, v9, v5, s[2:3]
	s_mov_b32 s2, 0xd000
	v_add_co_u32_e64 v6, s[2:3], s2, v0
	s_nop 1
	v_addc_co_u32_e64 v7, s[2:3], 0, v1, s[2:3]
	global_load_ushort v6, v[6:7], off offset:1552
	s_waitcnt vmcnt(0)
	v_lshlrev_b32_e32 v6, 16, v6
	v_add_f32_e32 v6, v3, v6
	v_max_f32_e32 v7, 0, v6
	v_mul_f32_e64 v6, |v6|, s59
	v_exp_f32_e32 v6, v6
	s_nop 0
	v_add_f32_e32 v6, 1.0, v6
	v_cmp_gt_f32_e64 s[2:3], s60, v6
	s_nop 1
	v_cndmask_b32_e64 v10, 0, 32, s[2:3]
	v_ldexp_f32 v6, v6, v10
	v_log_f32_e32 v6, v6
	s_nop 0
	v_mul_f32_e32 v10, 0x3f317217, v6
	v_fma_f32 v10, v6, s61, -v10
	v_fmac_f32_e32 v10, 0x3377d1cf, v6
	v_fmac_f32_e32 v10, 0x3f317217, v6
	v_cmp_lt_f32_e64 s[4:5], |v6|, s62
	s_nop 1
	v_cndmask_b32_e64 v6, v6, v10, s[4:5]
	v_cndmask_b32_e64 v10, 0, v186, s[2:3]
	v_sub_f32_e32 v6, v6, v10
	v_add_f32_e32 v6, v7, v6
	v_cmp_gt_u32_e64 s[2:3], 3, v70
	v_fma_f32 v7, v6, -v2, v8
	s_nop 0
	v_cndmask_b32_e64 v10, v7, v8, s[2:3]
	v_cmp_eq_u32_e64 s[2:3], 3, v70
	s_nop 1
	v_cndmask_b32_e64 v11, v9, v6, s[2:3]
	s_mov_b32 s2, 0x10000
	v_add_co_u32_e64 v8, s[2:3], s2, v0
	s_nop 1
	v_addc_co_u32_e64 v9, s[2:3], 0, v1, s[2:3]
	global_load_ushort v7, v[8:9], off offset:3088
	s_waitcnt vmcnt(0)
	v_lshlrev_b32_e32 v7, 16, v7
	v_add_f32_e32 v7, v3, v7
	v_max_f32_e32 v8, 0, v7
	v_mul_f32_e64 v7, |v7|, s59
	v_exp_f32_e32 v7, v7
	s_nop 0
	v_add_f32_e32 v7, 1.0, v7
	v_cmp_gt_f32_e64 s[2:3], s60, v7
	s_nop 1
	v_cndmask_b32_e64 v9, 0, 32, s[2:3]
	v_ldexp_f32 v7, v7, v9
	v_log_f32_e32 v7, v7
	s_nop 0
	v_mul_f32_e32 v9, 0x3f317217, v7
	v_fma_f32 v9, v7, s61, -v9
	v_fmac_f32_e32 v9, 0x3377d1cf, v7
	v_fmac_f32_e32 v9, 0x3f317217, v7
	v_cmp_lt_f32_e64 s[4:5], |v7|, s62
	s_nop 1
	v_cndmask_b32_e64 v7, v7, v9, s[4:5]
	v_cndmask_b32_e64 v9, 0, v186, s[2:3]
	v_sub_f32_e32 v7, v7, v9
	v_add_f32_e32 v7, v8, v7
	v_cmp_gt_u32_e64 s[2:3], 4, v70
	v_fma_f32 v8, v7, -v2, v10
	s_nop 0
	v_cndmask_b32_e64 v10, v8, v10, s[2:3]
	v_cmp_eq_u32_e64 s[2:3], 4, v70
	s_nop 1
	v_cndmask_b32_e64 v11, v11, v7, s[2:3]
	s_mov_b32 s2, 0x14000
	v_add_co_u32_e64 v8, s[2:3], s2, v0
	s_nop 1
	v_addc_co_u32_e64 v9, s[2:3], 0, v1, s[2:3]
	global_load_ushort v8, v[8:9], off offset:528
	s_waitcnt vmcnt(0)
	v_lshlrev_b32_e32 v8, 16, v8
	v_add_f32_e32 v8, v3, v8
	v_max_f32_e32 v9, 0, v8
	v_mul_f32_e64 v8, |v8|, s59
	v_exp_f32_e32 v8, v8
	s_nop 0
	v_add_f32_e32 v8, 1.0, v8
	v_cmp_gt_f32_e64 s[2:3], s60, v8
	s_nop 1
	v_cndmask_b32_e64 v12, 0, 32, s[2:3]
	v_ldexp_f32 v8, v8, v12
	v_log_f32_e32 v8, v8
	s_nop 0
	v_mul_f32_e32 v12, 0x3f317217, v8
	v_fma_f32 v12, v8, s61, -v12
	v_fmac_f32_e32 v12, 0x3377d1cf, v8
	v_fmac_f32_e32 v12, 0x3f317217, v8
	v_cmp_lt_f32_e64 s[4:5], |v8|, s62
	s_nop 1
	v_cndmask_b32_e64 v8, v8, v12, s[4:5]
	v_cndmask_b32_e64 v12, 0, v186, s[2:3]
	v_sub_f32_e32 v8, v8, v12
	v_add_f32_e32 v8, v9, v8
	v_cmp_gt_u32_e64 s[2:3], 5, v70
	v_fma_f32 v9, v8, -v2, v10
	s_nop 0
	v_cndmask_b32_e64 v12, v9, v10, s[2:3]
	v_cmp_eq_u32_e64 s[2:3], 5, v70
	s_nop 1
	v_cndmask_b32_e64 v13, v11, v8, s[2:3]
	s_mov_b32 s2, 0x17000
	v_add_co_u32_e64 v10, s[2:3], s2, v0
	s_nop 1
	v_addc_co_u32_e64 v11, s[2:3], 0, v1, s[2:3]
	global_load_ushort v9, v[10:11], off offset:2064
	s_waitcnt vmcnt(0)
	v_lshlrev_b32_e32 v9, 16, v9
	v_add_f32_e32 v9, v3, v9
	v_max_f32_e32 v10, 0, v9
	v_mul_f32_e64 v9, |v9|, s59
	v_exp_f32_e32 v9, v9
	s_nop 0
	v_add_f32_e32 v9, 1.0, v9
	v_cmp_gt_f32_e64 s[2:3], s60, v9
	s_nop 1
	v_cndmask_b32_e64 v11, 0, 32, s[2:3]
	v_ldexp_f32 v9, v9, v11
	v_log_f32_e32 v9, v9
	s_nop 0
	v_mul_f32_e32 v11, 0x3f317217, v9
	v_fma_f32 v11, v9, s61, -v11
	v_fmac_f32_e32 v11, 0x3377d1cf, v9
	v_fmac_f32_e32 v11, 0x3f317217, v9
	v_cmp_lt_f32_e64 s[4:5], |v9|, s62
	s_nop 1
	v_cndmask_b32_e64 v9, v9, v11, s[4:5]
	v_cndmask_b32_e64 v11, 0, v186, s[2:3]
	v_sub_f32_e32 v9, v9, v11
	v_add_f32_e32 v9, v10, v9
	v_cmp_gt_u32_e64 s[2:3], 6, v70
	v_fma_f32 v10, v9, -v2, v12
	s_nop 0
	v_cndmask_b32_e64 v10, v10, v12, s[2:3]
	v_cmp_eq_u32_e64 s[2:3], 6, v70
	s_nop 1
	v_cndmask_b32_e64 v11, v13, v9, s[2:3]
	s_mov_b32 s2, 0x1a000
	v_add_co_u32_e64 v0, s[2:3], s2, v0
	s_nop 1
	v_addc_co_u32_e64 v1, s[2:3], 0, v1, s[2:3]
	global_load_ushort v0, v[0:1], off offset:3600
	s_waitcnt vmcnt(0)
	v_lshlrev_b32_e32 v0, 16, v0
	v_add_f32_e32 v0, v3, v0
	v_max_f32_e32 v1, 0, v0
	v_mul_f32_e64 v0, |v0|, s59
	v_exp_f32_e32 v0, v0
	s_nop 0
	v_add_f32_e32 v0, 1.0, v0
	v_cmp_gt_f32_e64 s[2:3], s60, v0
	s_nop 1
	v_cndmask_b32_e64 v3, 0, 32, s[2:3]
	v_ldexp_f32 v0, v0, v3
	v_log_f32_e32 v0, v0
	s_nop 0
	v_mul_f32_e32 v3, 0x3f317217, v0
	v_fma_f32 v3, v0, s61, -v3
	v_fmac_f32_e32 v3, 0x3377d1cf, v0
	v_fmac_f32_e32 v3, 0x3f317217, v0
	v_cmp_lt_f32_e64 s[4:5], |v0|, s62
	s_nop 1
	v_cndmask_b32_e64 v0, v0, v3, s[4:5]
	v_cndmask_b32_e64 v3, 0, v186, s[2:3]
	v_sub_f32_e32 v0, v0, v3
	v_add_f32_e32 v0, v1, v0
	v_cmp_eq_u32_e64 s[2:3], 7, v70
	v_fma_f32 v1, v0, -v2, v10
	s_nop 0
	v_cndmask_b32_e64 v1, v10, v1, s[2:3]
	v_cndmask_b32_e64 v3, v11, v0, s[2:3]
	ds_write2st64_b32 v91, v1, v3 offset0:145 offset1:146
	s_and_b64 exec, exec, vcc
	s_cbranch_execz .LBB0_286
	v_mul_f32_e64 v1, v5, -v2
	v_mul_f32_e64 v3, v6, -v2
	v_add_f32_e32 v1, v4, v1
	v_mul_f32_e64 v5, v7, -v2
	v_add_f32_e32 v1, v1, v3
	v_mul_f32_e64 v6, v8, -v2
	v_add_f32_e32 v1, v1, v5
	v_mul_f32_e64 v7, v9, -v2
	v_add_f32_e32 v1, v1, v6
	v_mul_f32_e64 v0, v0, -v2
	v_add_f32_e32 v1, v1, v7
	v_add_f32_e32 v0, v1, v0
	v_lshl_add_u32 v1, v71, 2, 0
	ds_write_b32 v1, v0 offset:37632

.LBB0_603:
	s_or_b64 exec, exec, s[2:3]
	v_lshlrev_b32_e32 v0, 4, v68
	v_ashrrev_i32_e32 v5, 5, v68
	v_mov_b64_e32 v[8:9], s[28:29]
	v_and_b32_e32 v168, 0x1f0, v0
	v_mad_i64_i32 v[0:1], s[2:3], v5, s54, v[8:9]
	s_lshl_b32 s30, s71, 9
	v_lshl_add_u64 v[0:1], v[0:1], 0, s[30:31]
	v_lshl_add_u64 v[10:11], v[0:1], 0, v[168:169]
	v_add_co_u32_e32 v252, vcc, 0x1000, v10
	s_nop 1
	v_addc_co_u32_e32 v253, vcc, 0, v11, vcc
	global_load_dwordx4 v[20:23], v[252:253], off offset:-4096
	global_load_dwordx4 v[24:27], v[252:253], off offset:-2048
	global_load_dwordx4 v[28:31], v[252:253], off
	v_add_co_u32_e32 v252, vcc, 0x36000, v252
	s_nop 1
	v_addc_co_u32_e32 v253, vcc, 0, v253, vcc
	global_load_dwordx4 v[32:35], v[252:253], off offset:-4096
	global_load_dwordx4 v[36:39], v[252:253], off offset:-2048
	global_load_dwordx4 v[40:43], v[252:253], off
	v_add_co_u32_e32 v252, vcc, 0x36000, v252
	s_nop 1
	v_addc_co_u32_e32 v253, vcc, 0, v253, vcc
	global_load_dwordx4 v[44:47], v[252:253], off offset:-4096
	global_load_dwordx4 v[48:51], v[252:253], off offset:-2048
	global_load_dwordx4 v[52:55], v[252:253], off
	v_add_co_u32_e32 v252, vcc, 0x36000, v252
	s_nop 1
	v_addc_co_u32_e32 v253, vcc, 0, v253, vcc
	global_load_dwordx4 v[56:59], v[252:253], off offset:-4096
	global_load_dwordx4 v[60:63], v[252:253], off offset:-2048
	global_load_dwordx4 v[64:67], v[252:253], off
	v_add_u32_e32 v4, 0, v168
	s_movk_i32 s4, 0x210
	v_mad_u64_u32 v[12:13], s[2:3], v5, s4, v[4:5]
	v_add_u32_e32 v6, s53, v168
	v_ashrrev_i32_e32 v73, 6, v68
	v_and_b32_e32 v69, 15, v68
	v_lshlrev_b32_e32 v71, 5, v73
	s_movk_i32 s8, 0x210
	s_waitcnt vmcnt(11)
	ds_write_b128 v12, v[20:23]
	s_waitcnt vmcnt(10)
	ds_write_b128 v12, v[24:27] offset:33792
	v_add_co_u32_e32 v0, vcc, s63, v10
	v_mad_u64_u32 v[12:13], s[2:3], v5, s64, v[6:7]
	s_nop 0
	v_addc_co_u32_e32 v1, vcc, 0, v11, vcc
	s_waitcnt vmcnt(9)
	ds_write_b128 v12, v[28:31]
	v_add_u32_e32 v0, 0x200, v68
	v_ashrrev_i32_e32 v5, 5, v0
	v_mad_i64_i32 v[0:1], s[2:3], v5, s54, v[8:9]
	v_lshl_add_u64 v[0:1], v[0:1], 0, s[30:31]
	v_lshl_add_u64 v[10:11], v[0:1], 0, v[168:169]
	v_mad_u64_u32 v[12:13], s[2:3], v5, s4, v[4:5]
	s_waitcnt vmcnt(8)
	ds_write_b128 v12, v[32:35]
	s_waitcnt vmcnt(7)
	ds_write_b128 v12, v[36:39] offset:33792
	v_add_co_u32_e32 v0, vcc, s63, v10
	v_mad_u64_u32 v[12:13], s[2:3], v5, s64, v[6:7]
	s_nop 0
	v_addc_co_u32_e32 v1, vcc, 0, v11, vcc
	s_waitcnt vmcnt(6)
	ds_write_b128 v12, v[40:43]
	v_add_u32_e32 v0, 0x400, v68
	v_ashrrev_i32_e32 v5, 5, v0
	v_mad_i64_i32 v[0:1], s[2:3], v5, s54, v[8:9]
	v_lshl_add_u64 v[0:1], v[0:1], 0, s[30:31]
	v_lshl_add_u64 v[10:11], v[0:1], 0, v[168:169]
	v_mad_u64_u32 v[12:13], s[2:3], v5, s4, v[4:5]
	s_waitcnt vmcnt(5)
	ds_write_b128 v12, v[44:47]
	s_waitcnt vmcnt(4)
	ds_write_b128 v12, v[48:51] offset:33792
	v_add_co_u32_e32 v0, vcc, s63, v10
	v_mad_u64_u32 v[12:13], s[2:3], v5, s64, v[6:7]
	s_nop 0
	v_addc_co_u32_e32 v1, vcc, 0, v11, vcc
	s_waitcnt vmcnt(3)
	ds_write_b128 v12, v[52:55]
	v_add_u32_e32 v0, 0x600, v68
	v_ashrrev_i32_e32 v7, 5, v0
	v_mad_i64_i32 v[0:1], s[2:3], v7, s54, v[8:9]
	v_lshl_add_u64 v[0:1], v[0:1], 0, s[30:31]
	v_lshl_add_u64 v[8:9], v[0:1], 0, v[168:169]
	v_mad_u64_u32 v[4:5], s[2:3], v7, s4, v[4:5]
	s_waitcnt vmcnt(2)
	ds_write_b128 v4, v[56:59]
	s_waitcnt vmcnt(1)
	ds_write_b128 v4, v[60:63] offset:33792
	v_add_co_u32_e32 v0, vcc, s63, v8
	v_mad_u64_u32 v[4:5], s[2:3], v7, s64, v[6:7]
	s_nop 0
	v_addc_co_u32_e32 v1, vcc, 0, v9, vcc
	v_ashrrev_i32_e32 v8, 3, v68
	v_and_or_b32 v9, v71, 32, v69
	v_and_b32_e32 v20, -16, v8
	s_waitcnt vmcnt(0)
	ds_write_b128 v4, v[64:67]
	v_and_b32_e32 v1, 48, v70
	v_bfi_b32 v0, -16, v8, v68
	v_add_u32_e32 v4, 0, v1
	v_mad_u64_u32 v[18:19], s[2:3], v0, s4, v[4:5]
	s_waitcnt lgkmcnt(0)
	s_barrier
	ds_read_b128 v[0:3], v18
	v_mad_u32_u24 v19, v9, s4, v4
	ds_read_b128 v[4:7], v19 offset:33792
	ds_read_b128 v[10:13], v19 offset:42240
	s_waitcnt lgkmcnt(1)
	v_mfma_f32_16x16x32_bf16 v[4:7], v[0:3], v[4:7], 0
	s_add_i32 s4, 0, 0x1bd00
	s_waitcnt lgkmcnt(0)
	v_mfma_f32_16x16x32_bf16 v[0:3], v[0:3], v[10:13], 0
	ds_read_b128 v[10:13], v18 offset:64
	ds_read_b128 v[14:17], v19 offset:33856
	s_waitcnt lgkmcnt(0)
	v_mfma_f32_16x16x32_bf16 v[4:7], v[10:13], v[14:17], v[4:7]
	ds_read_b128 v[14:17], v19 offset:42304
	s_waitcnt lgkmcnt(0)
	v_mfma_f32_16x16x32_bf16 v[0:3], v[10:13], v[14:17], v[0:3]
	ds_read_b128 v[10:13], v18 offset:128
	ds_read_b128 v[14:17], v19 offset:33920
	s_waitcnt lgkmcnt(0)
	v_mfma_f32_16x16x32_bf16 v[4:7], v[10:13], v[14:17], v[4:7]
	ds_read_b128 v[14:17], v19 offset:42368
	s_waitcnt lgkmcnt(0)
	v_mfma_f32_16x16x32_bf16 v[0:3], v[10:13], v[14:17], v[0:3]
	ds_read_b128 v[10:13], v18 offset:192
	ds_read_b128 v[14:17], v19 offset:33984
	s_waitcnt lgkmcnt(0)
	v_mfma_f32_16x16x32_bf16 v[4:7], v[10:13], v[14:17], v[4:7]
	ds_read_b128 v[14:17], v19 offset:42432
	s_waitcnt lgkmcnt(0)
	v_mfma_f32_16x16x32_bf16 v[0:3], v[10:13], v[14:17], v[0:3]
	ds_read_b128 v[10:13], v18 offset:256
	ds_read_b128 v[14:17], v19 offset:34048
	s_waitcnt lgkmcnt(0)
	v_mfma_f32_16x16x32_bf16 v[4:7], v[10:13], v[14:17], v[4:7]
	ds_read_b128 v[14:17], v19 offset:42496
	s_waitcnt lgkmcnt(0)
	v_mfma_f32_16x16x32_bf16 v[0:3], v[10:13], v[14:17], v[0:3]
	ds_read_b128 v[10:13], v18 offset:320
	ds_read_b128 v[14:17], v19 offset:34112
	s_waitcnt lgkmcnt(0)
	v_mfma_f32_16x16x32_bf16 v[4:7], v[10:13], v[14:17], v[4:7]
	ds_read_b128 v[14:17], v19 offset:42560
	s_waitcnt lgkmcnt(0)
	v_mfma_f32_16x16x32_bf16 v[0:3], v[10:13], v[14:17], v[0:3]
	ds_read_b128 v[10:13], v18 offset:384
	ds_read_b128 v[14:17], v19 offset:34176
	s_waitcnt lgkmcnt(0)
	v_mfma_f32_16x16x32_bf16 v[4:7], v[10:13], v[14:17], v[4:7]
	ds_read_b128 v[14:17], v19 offset:42624
	s_waitcnt lgkmcnt(0)
	v_mfma_f32_16x16x32_bf16 v[0:3], v[10:13], v[14:17], v[0:3]
	ds_read_b128 v[10:13], v18 offset:448
	ds_read_b128 v[14:17], v19 offset:34240
	v_lshl_add_u32 v18, v9, 2, s4
	s_waitcnt lgkmcnt(0)
	v_mfma_f32_16x16x32_bf16 v[4:7], v[10:13], v[14:17], v[4:7]
	ds_read_b128 v[14:17], v19 offset:42688
	s_waitcnt lgkmcnt(0)
	v_mfma_f32_16x16x32_bf16 v[0:3], v[10:13], v[14:17], v[0:3]
	v_lshrrev_b32_e32 v10, 2, v70
	v_and_b32_e32 v72, 12, v10
	v_or_b32_e32 v11, v72, v20
	v_cmp_le_i32_e32 vcc, v9, v11
	v_mov_b32_e32 v15, 0
	v_lshl_add_u32 v10, v11, 2, 0
	v_mov_b32_e32 v13, 0
	s_and_saveexec_b64 s[2:3], vcc
	s_cbranch_execz .LBB0_605
	v_add_u32_e32 v12, 0x1bc00, v10
	v_add_u32_e32 v13, 0x1be00, v10
	ds_read_b32 v12, v12
	ds_read_b32 v13, v13
	s_waitcnt lgkmcnt(0)
	v_sub_f32_e32 v12, v12, v13
	ds_read_b32 v13, v18
	s_waitcnt lgkmcnt(0)
	v_add_f32_e32 v12, v12, v13
	v_mul_f32_e32 v12, 0x3fb8aa3b, v12
	v_exp_f32_e32 v12, v12
	s_nop 0
	v_mul_f32_e32 v4, v4, v12
	v_cvt_pk_bf16_f32 v13, v4, s0
